# grid barrier: first workgroup of each XCD to arrive issues one early L2 write-back before polling (run 1)
# baseline (speedup 1.0000x reference)
; __device__ __forceinline__ unsigned xb_ld(unsigned* p)              { return __hip_atomic_load(p, __ATOMIC_RELAXED, __HIP_MEMORY_SCOPE_AGENT); }
; __device__ __forceinline__ unsigned xb_add(unsigned* p, unsigned v) { return __hip_atomic_fetch_add(p, v, __ATOMIC_RELAXED, __HIP_MEMORY_SCOPE_AGENT); }
; #define XB_SPIN(cond, bar) do { unsigned _sp = 0; while (cond) { __builtin_amdgcn_s_sleep(1); \
;     if ((++_sp & 255u) == 0u) { if (xb_ld(&(bar)[XB_TMO])) break; if (_sp > XB_SPIN_CAP) { atomicAdd(&(bar)[XB_TMO], 1u); break; } } } } while (0)
; __device__ __forceinline__ void xcd_barrier(const XcdBarrier& b) {
;     ...
;         const unsigned old = xb_add(&bar[XB_XSUB(b.x)], 1u);
;         const unsigned gen = old / nloc;
;         if (old + 1u == (gen + 1u) * nloc) {
;             __builtin_amdgcn_fence(__ATOMIC_RELEASE, "agent");
;             asm volatile("s_waitcnt vmcnt(0)" ::: "memory");
;             const unsigned og = xb_add(&bar[XB_TOP], 1u);
;             const unsigned tg = og / nx;
;             if (og + 1u == (tg + 1u) * nx) xb_add(&bar[XB_TOPGEN], 1u);
;             else XB_SPIN(xb_ld(&bar[XB_TOPGEN]) == tg, bar);
;             __builtin_amdgcn_fence(__ATOMIC_ACQUIRE, "agent");
;             xb_add(&bar[XB_XGEN(b.x)], 1u);
;             asm volatile("s_waitcnt vmcnt(0)" ::: "memory");
;         } else {
;             XB_SPIN(xb_ld(&bar[XB_XGEN(b.x)]) == gen, bar);
;             __builtin_amdgcn_fence(__ATOMIC_ACQUIRE, "agent");
;             asm volatile("s_waitcnt vmcnt(0)" ::: "memory");
.LBB0_250:
	s_lshl_b32 s4, s74, 8
	s_add_u32 s4, s72, s4
	s_addc_u32 s5, s73, 0
	v_mov_b32_e32 v1, 0x1000
	v_mov_b32_e32 v3, 1
	global_atomic_add v3, v1, v3, s[4:5] offset:1024 sc0
	v_cvt_f32_u32_e32 v1, v2
	v_sub_u32_e32 v4, 0, v2
	v_rcp_iflag_f32_e32 v1, v1
	s_nop 0
	v_mul_f32_e32 v1, 0x4f7ffffe, v1
	v_cvt_u32_f32_e32 v1, v1
	v_mul_lo_u32 v4, v4, v1
	v_mul_hi_u32 v4, v1, v4
	v_add_u32_e32 v1, v1, v4
	s_waitcnt vmcnt(0)
	v_mul_hi_u32 v1, v3, v1
	v_mul_lo_u32 v4, v1, v2
	v_sub_u32_e32 v4, v3, v4
	v_add_u32_e32 v5, 1, v1
	v_cmp_ge_u32_e32 vcc, v4, v2
	v_add_u32_e32 v3, 1, v3
	s_nop 0
	v_cndmask_b32_e32 v1, v1, v5, vcc
	v_sub_u32_e32 v5, v4, v2
	v_cndmask_b32_e32 v4, v4, v5, vcc
	v_add_u32_e32 v5, 1, v1
	v_cmp_ge_u32_e32 vcc, v4, v2
	s_nop 1
	v_cndmask_b32_e32 v1, v1, v5, vcc
	v_mul_lo_u32 v4, v2, v1
	v_add_u32_e32 v2, v4, v2
	v_cmp_ne_u32_e32 vcc, v3, v2
	s_and_saveexec_b64 s[10:11], vcc
	s_xor_b64 s[10:11], exec, s[10:11]
	s_cbranch_execz .LBB0_264
	s_waitcnt lgkmcnt(0)
	v_add_u32_e32 v5, 1, v4
	v_cmp_eq_u32_e32 vcc, v3, v5
	s_cbranch_vccz .Lewb_11
	buffer_wbl2 sc1
.Lewb_11:
	v_mov_b32_e32 v0, 0x2000
	global_load_dword v0, v0, s[4:5] offset:1024 sc1
	s_add_u32 s16, s4, 0x2400
	s_addc_u32 s17, s5, 0
	s_waitcnt vmcnt(0)
	v_cmp_eq_u32_e32 vcc, v0, v1
	s_and_saveexec_b64 s[12:13], vcc
	s_cbranch_execz .LBB0_263
	s_add_u32 s14, s64, 0x2aa4200
	s_addc_u32 s15, s65, 0
	s_mov_b32 s28, 1
	s_mov_b64 s[18:19], 0
	v_mov_b32_e32 v0, 0
	s_branch .LBB0_254

; __device__ __forceinline__ unsigned xb_ld(unsigned* p)              { return __hip_atomic_load(p, __ATOMIC_RELAXED, __HIP_MEMORY_SCOPE_AGENT); }
; __device__ __forceinline__ unsigned xb_add(unsigned* p, unsigned v) { return __hip_atomic_fetch_add(p, v, __ATOMIC_RELAXED, __HIP_MEMORY_SCOPE_AGENT); }
; #define XB_SPIN(cond, bar) do { unsigned _sp = 0; while (cond) { __builtin_amdgcn_s_sleep(1); \
;     if ((++_sp & 255u) == 0u) { if (xb_ld(&(bar)[XB_TMO])) break; if (_sp > XB_SPIN_CAP) { atomicAdd(&(bar)[XB_TMO], 1u); break; } } } } while (0)
; __device__ __forceinline__ void xcd_barrier(const XcdBarrier& b) {
;     ...
;         const unsigned old = xb_add(&bar[XB_XSUB(b.x)], 1u);
;         const unsigned gen = old / nloc;
;         if (old + 1u == (gen + 1u) * nloc) {
;             __builtin_amdgcn_fence(__ATOMIC_RELEASE, "agent");
;             asm volatile("s_waitcnt vmcnt(0)" ::: "memory");
;             const unsigned og = xb_add(&bar[XB_TOP], 1u);
;             const unsigned tg = og / nx;
;             if (og + 1u == (tg + 1u) * nx) xb_add(&bar[XB_TOPGEN], 1u);
;             else XB_SPIN(xb_ld(&bar[XB_TOPGEN]) == tg, bar);
;             __builtin_amdgcn_fence(__ATOMIC_ACQUIRE, "agent");
;             xb_add(&bar[XB_XGEN(b.x)], 1u);
;             asm volatile("s_waitcnt vmcnt(0)" ::: "memory");
;         } else {
;             XB_SPIN(xb_ld(&bar[XB_XGEN(b.x)]) == gen, bar);
;             __builtin_amdgcn_fence(__ATOMIC_ACQUIRE, "agent");
;             asm volatile("s_waitcnt vmcnt(0)" ::: "memory");
.LBB0_410:
	s_lshl_b32 s4, s74, 8
	s_add_u32 s4, s72, s4
	s_addc_u32 s5, s73, 0
	v_mov_b32_e32 v1, 0x1000
	v_mov_b32_e32 v3, 1
	global_atomic_add v3, v1, v3, s[4:5] offset:1024 sc0
	v_cvt_f32_u32_e32 v1, v2
	v_sub_u32_e32 v4, 0, v2
	v_rcp_iflag_f32_e32 v1, v1
	s_nop 0
	v_mul_f32_e32 v1, 0x4f7ffffe, v1
	v_cvt_u32_f32_e32 v1, v1
	v_mul_lo_u32 v4, v4, v1
	v_mul_hi_u32 v4, v1, v4
	v_add_u32_e32 v1, v1, v4
	s_waitcnt vmcnt(0)
	v_mul_hi_u32 v1, v3, v1
	v_mul_lo_u32 v4, v1, v2
	v_sub_u32_e32 v4, v3, v4
	v_add_u32_e32 v5, 1, v1
	v_cmp_ge_u32_e32 vcc, v4, v2
	v_add_u32_e32 v3, 1, v3
	s_nop 0
	v_cndmask_b32_e32 v1, v1, v5, vcc
	v_sub_u32_e32 v5, v4, v2
	v_cndmask_b32_e32 v4, v4, v5, vcc
	v_add_u32_e32 v5, 1, v1
	v_cmp_ge_u32_e32 vcc, v4, v2
	s_nop 1
	v_cndmask_b32_e32 v1, v1, v5, vcc
	v_mul_lo_u32 v4, v2, v1
	v_add_u32_e32 v2, v4, v2
	v_cmp_ne_u32_e32 vcc, v3, v2
	s_and_saveexec_b64 s[8:9], vcc
	s_xor_b64 s[8:9], exec, s[8:9]
	s_cbranch_execz .LBB0_424
	s_waitcnt lgkmcnt(0)
	v_add_u32_e32 v5, 1, v4
	v_cmp_eq_u32_e32 vcc, v3, v5
	s_cbranch_vccz .Lewb_9
	buffer_wbl2 sc1
.Lewb_9:
	v_mov_b32_e32 v0, 0x2000
	global_load_dword v0, v0, s[4:5] offset:1024 sc1
	s_add_u32 s14, s4, 0x2400
	s_addc_u32 s15, s5, 0
	s_waitcnt vmcnt(0)
	v_cmp_eq_u32_e32 vcc, v0, v1
	s_and_saveexec_b64 s[10:11], vcc
	s_cbranch_execz .LBB0_423
	s_add_u32 s12, s64, 0x2aa4200
	s_addc_u32 s13, s65, 0
	s_mov_b32 s26, 1
	s_mov_b64 s[16:17], 0
	v_mov_b32_e32 v0, 0
	s_branch .LBB0_414

; __device__ __forceinline__ unsigned xb_ld(unsigned* p)              { return __hip_atomic_load(p, __ATOMIC_RELAXED, __HIP_MEMORY_SCOPE_AGENT); }
; __device__ __forceinline__ unsigned xb_add(unsigned* p, unsigned v) { return __hip_atomic_fetch_add(p, v, __ATOMIC_RELAXED, __HIP_MEMORY_SCOPE_AGENT); }
; #define XB_SPIN(cond, bar) do { unsigned _sp = 0; while (cond) { __builtin_amdgcn_s_sleep(1); \
;     if ((++_sp & 255u) == 0u) { if (xb_ld(&(bar)[XB_TMO])) break; if (_sp > XB_SPIN_CAP) { atomicAdd(&(bar)[XB_TMO], 1u); break; } } } } while (0)
; __device__ __forceinline__ void xcd_barrier(const XcdBarrier& b) {
;     ...
;         const unsigned old = xb_add(&bar[XB_XSUB(b.x)], 1u);
;         const unsigned gen = old / nloc;
;         if (old + 1u == (gen + 1u) * nloc) {
;             __builtin_amdgcn_fence(__ATOMIC_RELEASE, "agent");
;             asm volatile("s_waitcnt vmcnt(0)" ::: "memory");
;             const unsigned og = xb_add(&bar[XB_TOP], 1u);
;             const unsigned tg = og / nx;
;             if (og + 1u == (tg + 1u) * nx) xb_add(&bar[XB_TOPGEN], 1u);
;             else XB_SPIN(xb_ld(&bar[XB_TOPGEN]) == tg, bar);
;             __builtin_amdgcn_fence(__ATOMIC_ACQUIRE, "agent");
;             xb_add(&bar[XB_XGEN(b.x)], 1u);
;             asm volatile("s_waitcnt vmcnt(0)" ::: "memory");
;         } else {
;             XB_SPIN(xb_ld(&bar[XB_XGEN(b.x)]) == gen, bar);
;             __builtin_amdgcn_fence(__ATOMIC_ACQUIRE, "agent");
;             asm volatile("s_waitcnt vmcnt(0)" ::: "memory");
.LBB0_480:
	s_lshl_b32 s8, s74, 8
	s_add_u32 s8, s72, s8
	s_addc_u32 s9, s73, 0
	v_mov_b32_e32 v1, 0x1000
	v_mov_b32_e32 v3, 1
	global_atomic_add v3, v1, v3, s[8:9] offset:1024 sc0
	v_cvt_f32_u32_e32 v1, v2
	v_sub_u32_e32 v4, 0, v2
	v_rcp_iflag_f32_e32 v1, v1
	s_nop 0
	v_mul_f32_e32 v1, 0x4f7ffffe, v1
	v_cvt_u32_f32_e32 v1, v1
	v_mul_lo_u32 v4, v4, v1
	v_mul_hi_u32 v4, v1, v4
	v_add_u32_e32 v1, v1, v4
	s_waitcnt vmcnt(0)
	v_mul_hi_u32 v1, v3, v1
	v_mul_lo_u32 v4, v1, v2
	v_sub_u32_e32 v4, v3, v4
	v_add_u32_e32 v5, 1, v1
	v_cmp_ge_u32_e32 vcc, v4, v2
	v_add_u32_e32 v3, 1, v3
	s_nop 0
	v_cndmask_b32_e32 v1, v1, v5, vcc
	v_sub_u32_e32 v5, v4, v2
	v_cndmask_b32_e32 v4, v4, v5, vcc
	v_add_u32_e32 v5, 1, v1
	v_cmp_ge_u32_e32 vcc, v4, v2
	s_nop 1
	v_cndmask_b32_e32 v1, v1, v5, vcc
	v_mul_lo_u32 v4, v2, v1
	v_add_u32_e32 v2, v4, v2
	v_cmp_ne_u32_e32 vcc, v3, v2
	s_and_saveexec_b64 s[10:11], vcc
	s_xor_b64 s[10:11], exec, s[10:11]
	s_cbranch_execz .LBB0_494
	s_waitcnt lgkmcnt(0)
	v_add_u32_e32 v5, 1, v4
	v_cmp_eq_u32_e32 vcc, v3, v5
	s_cbranch_vccz .Lewb_8
	buffer_wbl2 sc1
.Lewb_8:
	v_mov_b32_e32 v0, 0x2000
	global_load_dword v0, v0, s[8:9] offset:1024 sc1
	s_add_u32 s16, s8, 0x2400
	s_addc_u32 s17, s9, 0
	s_waitcnt vmcnt(0)
	v_cmp_eq_u32_e32 vcc, v0, v1
	s_and_saveexec_b64 s[12:13], vcc
	s_cbranch_execz .LBB0_493
	s_add_u32 s14, s64, 0x2aa4200
	s_addc_u32 s15, s65, 0
	s_mov_b32 s28, 1
	s_mov_b64 s[18:19], 0
	v_mov_b32_e32 v0, 0
	s_branch .LBB0_484

; __device__ __forceinline__ unsigned xb_ld(unsigned* p)              { return __hip_atomic_load(p, __ATOMIC_RELAXED, __HIP_MEMORY_SCOPE_AGENT); }
; __device__ __forceinline__ unsigned xb_add(unsigned* p, unsigned v) { return __hip_atomic_fetch_add(p, v, __ATOMIC_RELAXED, __HIP_MEMORY_SCOPE_AGENT); }
; #define XB_SPIN(cond, bar) do { unsigned _sp = 0; while (cond) { __builtin_amdgcn_s_sleep(1); \
;     if ((++_sp & 255u) == 0u) { if (xb_ld(&(bar)[XB_TMO])) break; if (_sp > XB_SPIN_CAP) { atomicAdd(&(bar)[XB_TMO], 1u); break; } } } } while (0)
; __device__ __forceinline__ void xcd_barrier(const XcdBarrier& b) {
;     ...
;         const unsigned old = xb_add(&bar[XB_XSUB(b.x)], 1u);
;         const unsigned gen = old / nloc;
;         if (old + 1u == (gen + 1u) * nloc) {
;             __builtin_amdgcn_fence(__ATOMIC_RELEASE, "agent");
;             asm volatile("s_waitcnt vmcnt(0)" ::: "memory");
;             const unsigned og = xb_add(&bar[XB_TOP], 1u);
;             const unsigned tg = og / nx;
;             if (og + 1u == (tg + 1u) * nx) xb_add(&bar[XB_TOPGEN], 1u);
;             else XB_SPIN(xb_ld(&bar[XB_TOPGEN]) == tg, bar);
;             __builtin_amdgcn_fence(__ATOMIC_ACQUIRE, "agent");
;             xb_add(&bar[XB_XGEN(b.x)], 1u);
;             asm volatile("s_waitcnt vmcnt(0)" ::: "memory");
;         } else {
;             XB_SPIN(xb_ld(&bar[XB_XGEN(b.x)]) == gen, bar);
;             __builtin_amdgcn_fence(__ATOMIC_ACQUIRE, "agent");
;             asm volatile("s_waitcnt vmcnt(0)" ::: "memory");
.LBB0_581:
	s_lshl_b32 s4, s74, 8
	s_add_u32 s4, s72, s4
	s_addc_u32 s5, s73, 0
	v_mov_b32_e32 v1, 0x1000
	v_mov_b32_e32 v3, 1
	global_atomic_add v3, v1, v3, s[4:5] offset:1024 sc0
	v_cvt_f32_u32_e32 v1, v2
	v_sub_u32_e32 v4, 0, v2
	v_rcp_iflag_f32_e32 v1, v1
	s_nop 0
	v_mul_f32_e32 v1, 0x4f7ffffe, v1
	v_cvt_u32_f32_e32 v1, v1
	v_mul_lo_u32 v4, v4, v1
	v_mul_hi_u32 v4, v1, v4
	v_add_u32_e32 v1, v1, v4
	s_waitcnt vmcnt(0)
	v_mul_hi_u32 v1, v3, v1
	v_mul_lo_u32 v4, v1, v2
	v_sub_u32_e32 v4, v3, v4
	v_add_u32_e32 v5, 1, v1
	v_cmp_ge_u32_e32 vcc, v4, v2
	v_add_u32_e32 v3, 1, v3
	s_nop 0
	v_cndmask_b32_e32 v1, v1, v5, vcc
	v_sub_u32_e32 v5, v4, v2
	v_cndmask_b32_e32 v4, v4, v5, vcc
	v_add_u32_e32 v5, 1, v1
	v_cmp_ge_u32_e32 vcc, v4, v2
	s_nop 1
	v_cndmask_b32_e32 v1, v1, v5, vcc
	v_mul_lo_u32 v4, v2, v1
	v_add_u32_e32 v2, v4, v2
	v_cmp_ne_u32_e32 vcc, v3, v2
	s_and_saveexec_b64 s[6:7], vcc
	s_xor_b64 s[6:7], exec, s[6:7]
	s_cbranch_execz .LBB0_595
	s_waitcnt lgkmcnt(0)
	v_add_u32_e32 v5, 1, v4
	v_cmp_eq_u32_e32 vcc, v3, v5
	s_cbranch_vccz .Lewb_7
	buffer_wbl2 sc1
.Lewb_7:
	v_mov_b32_e32 v0, 0x2000
	global_load_dword v0, v0, s[4:5] offset:1024 sc1
	s_add_u32 s12, s4, 0x2400
	s_addc_u32 s13, s5, 0
	s_waitcnt vmcnt(0)
	v_cmp_eq_u32_e32 vcc, v0, v1
	s_and_saveexec_b64 s[8:9], vcc
	s_cbranch_execz .LBB0_594
	s_add_u32 s10, s64, 0x2aa4200
	s_addc_u32 s11, s65, 0
	s_mov_b32 s24, 1
	s_mov_b64 s[14:15], 0
	v_mov_b32_e32 v0, 0
	s_branch .LBB0_585

; __device__ __forceinline__ unsigned xb_ld(unsigned* p)              { return __hip_atomic_load(p, __ATOMIC_RELAXED, __HIP_MEMORY_SCOPE_AGENT); }
; __device__ __forceinline__ unsigned xb_add(unsigned* p, unsigned v) { return __hip_atomic_fetch_add(p, v, __ATOMIC_RELAXED, __HIP_MEMORY_SCOPE_AGENT); }
; #define XB_SPIN(cond, bar) do { unsigned _sp = 0; while (cond) { __builtin_amdgcn_s_sleep(1); \
;     if ((++_sp & 255u) == 0u) { if (xb_ld(&(bar)[XB_TMO])) break; if (_sp > XB_SPIN_CAP) { atomicAdd(&(bar)[XB_TMO], 1u); break; } } } } while (0)
; __device__ __forceinline__ void xcd_barrier(const XcdBarrier& b) {
;     ...
;         const unsigned old = xb_add(&bar[XB_XSUB(b.x)], 1u);
;         const unsigned gen = old / nloc;
;         if (old + 1u == (gen + 1u) * nloc) {
;             __builtin_amdgcn_fence(__ATOMIC_RELEASE, "agent");
;             asm volatile("s_waitcnt vmcnt(0)" ::: "memory");
;             const unsigned og = xb_add(&bar[XB_TOP], 1u);
;             const unsigned tg = og / nx;
;             if (og + 1u == (tg + 1u) * nx) xb_add(&bar[XB_TOPGEN], 1u);
;             else XB_SPIN(xb_ld(&bar[XB_TOPGEN]) == tg, bar);
;             __builtin_amdgcn_fence(__ATOMIC_ACQUIRE, "agent");
;             xb_add(&bar[XB_XGEN(b.x)], 1u);
;             asm volatile("s_waitcnt vmcnt(0)" ::: "memory");
;         } else {
;             XB_SPIN(xb_ld(&bar[XB_XGEN(b.x)]) == gen, bar);
;             __builtin_amdgcn_fence(__ATOMIC_ACQUIRE, "agent");
;             asm volatile("s_waitcnt vmcnt(0)" ::: "memory");
.LBB0_1101:
	s_lshl_b32 s6, s74, 8
	s_add_u32 s6, s72, s6
	s_addc_u32 s7, s73, 0
	v_mov_b32_e32 v1, 0x1000
	v_mov_b32_e32 v3, 1
	global_atomic_add v3, v1, v3, s[6:7] offset:1024 sc0
	v_cvt_f32_u32_e32 v1, v2
	v_sub_u32_e32 v4, 0, v2
	v_rcp_iflag_f32_e32 v1, v1
	s_nop 0
	v_mul_f32_e32 v1, 0x4f7ffffe, v1
	v_cvt_u32_f32_e32 v1, v1
	v_mul_lo_u32 v4, v4, v1
	v_mul_hi_u32 v4, v1, v4
	v_add_u32_e32 v1, v1, v4
	s_waitcnt vmcnt(0)
	v_mul_hi_u32 v1, v3, v1
	v_mul_lo_u32 v4, v1, v2
	v_sub_u32_e32 v4, v3, v4
	v_add_u32_e32 v5, 1, v1
	v_cmp_ge_u32_e32 vcc, v4, v2
	v_add_u32_e32 v3, 1, v3
	s_nop 0
	v_cndmask_b32_e32 v1, v1, v5, vcc
	v_sub_u32_e32 v5, v4, v2
	v_cndmask_b32_e32 v4, v4, v5, vcc
	v_add_u32_e32 v5, 1, v1
	v_cmp_ge_u32_e32 vcc, v4, v2
	s_nop 1
	v_cndmask_b32_e32 v1, v1, v5, vcc
	v_mul_lo_u32 v4, v2, v1
	v_add_u32_e32 v2, v4, v2
	v_cmp_ne_u32_e32 vcc, v3, v2
	s_and_saveexec_b64 s[8:9], vcc
	s_xor_b64 s[8:9], exec, s[8:9]
	s_cbranch_execz .LBB0_1115
	s_waitcnt lgkmcnt(0)
	v_add_u32_e32 v5, 1, v4
	v_cmp_eq_u32_e32 vcc, v3, v5
	s_cbranch_vccz .Lewb_2
	buffer_wbl2 sc1
.Lewb_2:
	v_mov_b32_e32 v0, 0x2000
	global_load_dword v0, v0, s[6:7] offset:1024 sc1
	s_add_u32 s14, s6, 0x2400
	s_addc_u32 s15, s7, 0
	s_waitcnt vmcnt(0)
	v_cmp_eq_u32_e32 vcc, v0, v1
	s_and_saveexec_b64 s[10:11], vcc
	s_cbranch_execz .LBB0_1114
	s_add_u32 s12, s64, 0x2aa4200
	s_addc_u32 s13, s65, 0
	s_mov_b32 s26, 1
	s_mov_b64 s[16:17], 0
	v_mov_b32_e32 v0, 0
	s_branch .LBB0_1105
